# U pass: dot chains of row pairs interleaved (4 independent accumulators)
# baseline (speedup 1.0000x reference)
; __device__ __forceinline__ void u_compute(const u32x4 (&w)[16], const PeerVisit& v, int* pd, int lane) {
;     ...
;     for (int it = 0; it < 16; ++it) {
;         int tl = 0, th = 0;
;         tl = __builtin_amdgcn_sdot4((int)(w[it].x & 0x0F0F0F0Fu), (int)v.x.x, tl, false);  th = __builtin_amdgcn_sdot4((int)(w[it].x & 0xF0F0F0F0u), (int)v.x.y, th, false);
;         tl = __builtin_amdgcn_sdot4((int)(w[it].y & 0x0F0F0F0Fu), (int)v.x.z, tl, false);  th = __builtin_amdgcn_sdot4((int)(w[it].y & 0xF0F0F0F0u), (int)v.x.w, th, false);
;         tl = __builtin_amdgcn_sdot4((int)(w[it].z & 0x0F0F0F0Fu), (int)v.x2.x, tl, false); th = __builtin_amdgcn_sdot4((int)(w[it].z & 0xF0F0F0F0u), (int)v.x2.y, th, false);
;         tl = __builtin_amdgcn_sdot4((int)(w[it].w & 0x0F0F0F0Fu), (int)v.x2.z, tl, false); th = __builtin_amdgcn_sdot4((int)(w[it].w & 0xF0F0F0F0u), (int)v.x2.w, th, false);
;         const int t = tl * 16 + th;
;         d[it] = dpp_add8(t);
; template <bool VPASS>
; __device__ __forceinline__ void peer_pass(Frame& F, int c, int rank, int nblk) {
;     ...
;     for (int v = 0; v < nvis; v += 2) {
;         const int tok = t0 + v * step;
;         asm volatile("" : "+v"(lane));
;         PeerVisit vn = va;
;         if (v + 1 < nvis) rows16_load(wb, T, vb, lane);
;         if (v + 2 < nvis) vn = visit_load<VPASS>(F.ws, FQc, tok + 2 * step, lane);
;         if (VPASS) v_compute(wa, va, PO + (size_t)tok * D, lane); else u_compute(wa, va, PD + (size_t)tok * 128, lane);
.Lmy_u_loop:
	v_lshl_add_u32 v180, v132, 7, v1
	v_lshl_add_u32 v181, v133, 7, v1
	v_lshl_add_u32 v182, v134, 7, v1
	v_lshl_add_u32 v183, v135, 7, v1
	v_lshl_add_u32 v184, v136, 7, v1
	v_lshl_add_u32 v185, v137, 7, v1
	v_lshl_add_u32 v186, v138, 7, v1
	v_lshl_add_u32 v187, v139, 7, v1
	v_lshl_add_u32 v188, v140, 7, v1
	v_lshl_add_u32 v189, v141, 7, v1
	v_lshl_add_u32 v190, v142, 7, v1
	v_lshl_add_u32 v191, v143, 7, v1
	v_lshl_add_u32 v192, v144, 7, v1
	v_lshl_add_u32 v193, v145, 7, v1
	v_lshl_add_u32 v194, v146, 7, v1
	v_lshl_add_u32 v195, v147, 7, v1
	s_add_i32 s38, s38, s39
	s_cmp_lt_i32 s38, 0x8000
	s_cselect_b32 s63, s48, 0
	s_cselect_b32 s71, s49, 0
	s_add_u32 s42, s42, s63
	s_addc_u32 s43, s43, 0
	s_add_u32 s44, s44, s71
	s_addc_u32 s45, s45, 0
	global_load_dwordx4 v[132:135], v0, s[42:43]
	global_load_dwordx4 v[136:139], v0, s[42:43] offset:16
	global_load_dwordx4 v[140:143], v0, s[42:43] offset:32
	global_load_dwordx4 v[144:147], v0, s[42:43] offset:48
	global_load_dwordx4 v[68:71], v180, s[40:41]
	global_load_dwordx4 v[72:75], v181, s[40:41]
	global_load_dwordx4 v[76:79], v182, s[40:41]
	global_load_dwordx4 v[80:83], v183, s[40:41]
	global_load_dwordx4 v[84:87], v184, s[40:41]
	global_load_dwordx4 v[88:91], v185, s[40:41]
	global_load_dwordx4 v[92:95], v186, s[40:41]
	global_load_dwordx4 v[96:99], v187, s[40:41]
	global_load_dwordx4 v[100:103], v188, s[40:41]
	global_load_dwordx4 v[104:107], v189, s[40:41]
	global_load_dwordx4 v[108:111], v190, s[40:41]
	global_load_dwordx4 v[112:115], v191, s[40:41]
	global_load_dwordx4 v[116:119], v192, s[40:41]
	global_load_dwordx4 v[120:123], v193, s[40:41]
	global_load_dwordx4 v[124:127], v194, s[40:41]
	global_load_dwordx4 v[128:131], v195, s[40:41]
	s_waitcnt vmcnt(38)
	v_and_b32_e32 v180, s61, v4
	v_and_b32_e32 v4, s62, v4
	v_and_b32_e32 v181, s61, v5
	v_and_b32_e32 v5, s62, v5
	v_and_b32_e32 v182, s61, v6
	v_and_b32_e32 v6, s62, v6
	v_and_b32_e32 v183, s61, v7
	v_and_b32_e32 v7, s62, v7
	v_and_b32_e32 v188, s61, v8
	v_and_b32_e32 v8, s62, v8
	v_and_b32_e32 v189, s61, v9
	v_and_b32_e32 v9, s62, v9
	v_and_b32_e32 v190, s61, v10
	v_and_b32_e32 v10, s62, v10
	v_and_b32_e32 v191, s61, v11
	v_and_b32_e32 v11, s62, v11
	v_dot4_i32_i8 v196, v180, v164, 0
	v_dot4_i32_i8 v197, v4, v165, 0
	v_dot4_i32_i8 v198, v188, v164, 0
	v_dot4_i32_i8 v199, v8, v165, 0
	v_dot4_i32_i8 v196, v181, v166, v196
	v_dot4_i32_i8 v197, v5, v167, v197
	v_dot4_i32_i8 v198, v189, v166, v198
	v_dot4_i32_i8 v199, v9, v167, v199
	v_dot4_i32_i8 v196, v182, v168, v196
	v_dot4_i32_i8 v197, v6, v169, v197
	v_dot4_i32_i8 v198, v190, v168, v198
	v_dot4_i32_i8 v199, v10, v169, v199
	v_dot4_i32_i8 v196, v183, v170, v196
	v_dot4_i32_i8 v197, v7, v171, v197
	v_dot4_i32_i8 v198, v191, v170, v198
	v_dot4_i32_i8 v199, v11, v171, v199
	s_waitcnt vmcnt(36)
	v_and_b32_e32 v180, s61, v12
	v_and_b32_e32 v12, s62, v12
	v_and_b32_e32 v181, s61, v13
	v_and_b32_e32 v13, s62, v13
	v_and_b32_e32 v182, s61, v14
	v_and_b32_e32 v14, s62, v14
	v_and_b32_e32 v183, s61, v15
	v_and_b32_e32 v15, s62, v15
	v_lshl_add_u32 v148, v196, 4, v197
	v_lshl_add_u32 v149, v198, 4, v199
	v_and_b32_e32 v188, s61, v16
	v_and_b32_e32 v16, s62, v16
	v_and_b32_e32 v189, s61, v17
	v_and_b32_e32 v17, s62, v17
	v_and_b32_e32 v190, s61, v18
	v_and_b32_e32 v18, s62, v18
	v_and_b32_e32 v191, s61, v19
	v_and_b32_e32 v19, s62, v19
	v_dot4_i32_i8 v196, v180, v164, 0
	v_dot4_i32_i8 v197, v12, v165, 0
	v_dot4_i32_i8 v198, v188, v164, 0
	v_dot4_i32_i8 v199, v16, v165, 0
	v_dot4_i32_i8 v196, v181, v166, v196
	v_dot4_i32_i8 v197, v13, v167, v197
	v_dot4_i32_i8 v198, v189, v166, v198
	v_dot4_i32_i8 v199, v17, v167, v199
	v_dot4_i32_i8 v196, v182, v168, v196
	v_dot4_i32_i8 v197, v14, v169, v197
	v_dot4_i32_i8 v198, v190, v168, v198
	v_dot4_i32_i8 v199, v18, v169, v199
	v_dot4_i32_i8 v196, v183, v170, v196
	v_dot4_i32_i8 v197, v15, v171, v197
	v_dot4_i32_i8 v198, v191, v170, v198
	v_dot4_i32_i8 v199, v19, v171, v199
	s_waitcnt vmcnt(34)
	v_and_b32_e32 v180, s61, v20
	v_and_b32_e32 v20, s62, v20
	v_and_b32_e32 v181, s61, v21
	v_and_b32_e32 v21, s62, v21
	v_and_b32_e32 v182, s61, v22
	v_and_b32_e32 v22, s62, v22
	v_and_b32_e32 v183, s61, v23
	v_and_b32_e32 v23, s62, v23
	v_lshl_add_u32 v150, v196, 4, v197
	v_lshl_add_u32 v151, v198, 4, v199
	v_and_b32_e32 v188, s61, v24
	v_and_b32_e32 v24, s62, v24
	v_and_b32_e32 v189, s61, v25
	v_and_b32_e32 v25, s62, v25
	v_and_b32_e32 v190, s61, v26
	v_and_b32_e32 v26, s62, v26
	v_and_b32_e32 v191, s61, v27
	v_and_b32_e32 v27, s62, v27
	v_dot4_i32_i8 v196, v180, v164, 0
	v_dot4_i32_i8 v197, v20, v165, 0
	v_dot4_i32_i8 v198, v188, v164, 0
	v_dot4_i32_i8 v199, v24, v165, 0
	v_dot4_i32_i8 v196, v181, v166, v196
	v_dot4_i32_i8 v197, v21, v167, v197
	v_dot4_i32_i8 v198, v189, v166, v198
	v_dot4_i32_i8 v199, v25, v167, v199
	v_dot4_i32_i8 v196, v182, v168, v196
	v_dot4_i32_i8 v197, v22, v169, v197
	v_dot4_i32_i8 v198, v190, v168, v198
	v_dot4_i32_i8 v199, v26, v169, v199
	v_dot4_i32_i8 v196, v183, v170, v196
	v_dot4_i32_i8 v197, v23, v171, v197
	v_dot4_i32_i8 v198, v191, v170, v198
	v_dot4_i32_i8 v199, v27, v171, v199
	s_waitcnt vmcnt(32)
; __device__ __forceinline__ void u_compute(const u32x4 (&w)[16], const PeerVisit& v, int* pd, int lane) {
;     ...
;     for (int it = 0; it < 16; ++it) {
;         int tl = 0, th = 0;
;         tl = __builtin_amdgcn_sdot4((int)(w[it].x & 0x0F0F0F0Fu), (int)v.x.x, tl, false);  th = __builtin_amdgcn_sdot4((int)(w[it].x & 0xF0F0F0F0u), (int)v.x.y, th, false);
;         tl = __builtin_amdgcn_sdot4((int)(w[it].y & 0x0F0F0F0Fu), (int)v.x.z, tl, false);  th = __builtin_amdgcn_sdot4((int)(w[it].y & 0xF0F0F0F0u), (int)v.x.w, th, false);
;         tl = __builtin_amdgcn_sdot4((int)(w[it].z & 0x0F0F0F0Fu), (int)v.x2.x, tl, false); th = __builtin_amdgcn_sdot4((int)(w[it].z & 0xF0F0F0F0u), (int)v.x2.y, th, false);
;         tl = __builtin_amdgcn_sdot4((int)(w[it].w & 0x0F0F0F0Fu), (int)v.x2.z, tl, false); th = __builtin_amdgcn_sdot4((int)(w[it].w & 0xF0F0F0F0u), (int)v.x2.w, th, false);
;         const int t = tl * 16 + th;
;         d[it] = dpp_add8(t);
	v_and_b32_e32 v180, s61, v28
	v_and_b32_e32 v28, s62, v28
	v_and_b32_e32 v181, s61, v29
	v_and_b32_e32 v29, s62, v29
	v_and_b32_e32 v182, s61, v30
	v_and_b32_e32 v30, s62, v30
	v_and_b32_e32 v183, s61, v31
	v_and_b32_e32 v31, s62, v31
	v_lshl_add_u32 v152, v196, 4, v197
	v_lshl_add_u32 v153, v198, 4, v199
	v_and_b32_e32 v188, s61, v32
	v_and_b32_e32 v32, s62, v32
	v_and_b32_e32 v189, s61, v33
	v_and_b32_e32 v33, s62, v33
	v_and_b32_e32 v190, s61, v34
	v_and_b32_e32 v34, s62, v34
	v_and_b32_e32 v191, s61, v35
	v_and_b32_e32 v35, s62, v35
	v_dot4_i32_i8 v196, v180, v164, 0
	v_dot4_i32_i8 v197, v28, v165, 0
	v_dot4_i32_i8 v198, v188, v164, 0
	v_dot4_i32_i8 v199, v32, v165, 0
	v_dot4_i32_i8 v196, v181, v166, v196
	v_dot4_i32_i8 v197, v29, v167, v197
	v_dot4_i32_i8 v198, v189, v166, v198
	v_dot4_i32_i8 v199, v33, v167, v199
	v_dot4_i32_i8 v196, v182, v168, v196
	v_dot4_i32_i8 v197, v30, v169, v197
	v_dot4_i32_i8 v198, v190, v168, v198
	v_dot4_i32_i8 v199, v34, v169, v199
	v_dot4_i32_i8 v196, v183, v170, v196
	v_dot4_i32_i8 v197, v31, v171, v197
	v_dot4_i32_i8 v198, v191, v170, v198
	v_dot4_i32_i8 v199, v35, v171, v199
	s_waitcnt vmcnt(30)
	v_and_b32_e32 v180, s61, v36
	v_and_b32_e32 v36, s62, v36
	v_and_b32_e32 v181, s61, v37
	v_and_b32_e32 v37, s62, v37
	v_and_b32_e32 v182, s61, v38
	v_and_b32_e32 v38, s62, v38
	v_and_b32_e32 v183, s61, v39
	v_and_b32_e32 v39, s62, v39
	v_lshl_add_u32 v154, v196, 4, v197
	v_lshl_add_u32 v155, v198, 4, v199
	v_and_b32_e32 v188, s61, v40
	v_and_b32_e32 v40, s62, v40
	v_and_b32_e32 v189, s61, v41
	v_and_b32_e32 v41, s62, v41
	v_and_b32_e32 v190, s61, v42
	v_and_b32_e32 v42, s62, v42
	v_and_b32_e32 v191, s61, v43
	v_and_b32_e32 v43, s62, v43
	v_dot4_i32_i8 v196, v180, v164, 0
	v_dot4_i32_i8 v197, v36, v165, 0
	v_dot4_i32_i8 v198, v188, v164, 0
	v_dot4_i32_i8 v199, v40, v165, 0
	v_dot4_i32_i8 v196, v181, v166, v196
	v_dot4_i32_i8 v197, v37, v167, v197
	v_dot4_i32_i8 v198, v189, v166, v198
	v_dot4_i32_i8 v199, v41, v167, v199
	v_dot4_i32_i8 v196, v182, v168, v196
	v_dot4_i32_i8 v197, v38, v169, v197
	v_dot4_i32_i8 v198, v190, v168, v198
	v_dot4_i32_i8 v199, v42, v169, v199
	v_dot4_i32_i8 v196, v183, v170, v196
	v_dot4_i32_i8 v197, v39, v171, v197
	v_dot4_i32_i8 v198, v191, v170, v198
	v_dot4_i32_i8 v199, v43, v171, v199
	s_waitcnt vmcnt(28)
	v_and_b32_e32 v180, s61, v44
	v_and_b32_e32 v44, s62, v44
	v_and_b32_e32 v181, s61, v45
	v_and_b32_e32 v45, s62, v45
	v_and_b32_e32 v182, s61, v46
	v_and_b32_e32 v46, s62, v46
	v_and_b32_e32 v183, s61, v47
	v_and_b32_e32 v47, s62, v47
	v_lshl_add_u32 v156, v196, 4, v197
	v_lshl_add_u32 v157, v198, 4, v199
	v_and_b32_e32 v188, s61, v48
	v_and_b32_e32 v48, s62, v48
	v_and_b32_e32 v189, s61, v49
	v_and_b32_e32 v49, s62, v49
	v_and_b32_e32 v190, s61, v50
	v_and_b32_e32 v50, s62, v50
	v_and_b32_e32 v191, s61, v51
	v_and_b32_e32 v51, s62, v51
	v_dot4_i32_i8 v196, v180, v164, 0
	v_dot4_i32_i8 v197, v44, v165, 0
	v_dot4_i32_i8 v198, v188, v164, 0
	v_dot4_i32_i8 v199, v48, v165, 0
	v_dot4_i32_i8 v196, v181, v166, v196
	v_dot4_i32_i8 v197, v45, v167, v197
	v_dot4_i32_i8 v198, v189, v166, v198
	v_dot4_i32_i8 v199, v49, v167, v199
	v_dot4_i32_i8 v196, v182, v168, v196
	v_dot4_i32_i8 v197, v46, v169, v197
	v_dot4_i32_i8 v198, v190, v168, v198
	v_dot4_i32_i8 v199, v50, v169, v199
	v_dot4_i32_i8 v196, v183, v170, v196
	v_dot4_i32_i8 v197, v47, v171, v197
	v_dot4_i32_i8 v198, v191, v170, v198
	v_dot4_i32_i8 v199, v51, v171, v199
	s_waitcnt vmcnt(26)
	v_and_b32_e32 v180, s61, v52
	v_and_b32_e32 v52, s62, v52
	v_and_b32_e32 v181, s61, v53
	v_and_b32_e32 v53, s62, v53
	v_and_b32_e32 v182, s61, v54
	v_and_b32_e32 v54, s62, v54
	v_and_b32_e32 v183, s61, v55
	v_and_b32_e32 v55, s62, v55
	v_lshl_add_u32 v158, v196, 4, v197
	v_lshl_add_u32 v159, v198, 4, v199
	v_and_b32_e32 v188, s61, v56
	v_and_b32_e32 v56, s62, v56
	v_and_b32_e32 v189, s61, v57
	v_and_b32_e32 v57, s62, v57
	v_and_b32_e32 v190, s61, v58
	v_and_b32_e32 v58, s62, v58
	v_and_b32_e32 v191, s61, v59
	v_and_b32_e32 v59, s62, v59
	v_dot4_i32_i8 v196, v180, v164, 0
	v_dot4_i32_i8 v197, v52, v165, 0
	v_dot4_i32_i8 v198, v188, v164, 0
	v_dot4_i32_i8 v199, v56, v165, 0
	v_dot4_i32_i8 v196, v181, v166, v196
	v_dot4_i32_i8 v197, v53, v167, v197
	v_dot4_i32_i8 v198, v189, v166, v198
	v_dot4_i32_i8 v199, v57, v167, v199
	v_dot4_i32_i8 v196, v182, v168, v196
	v_dot4_i32_i8 v197, v54, v169, v197
	v_dot4_i32_i8 v198, v190, v168, v198
	v_dot4_i32_i8 v199, v58, v169, v199
	v_dot4_i32_i8 v196, v183, v170, v196
	v_dot4_i32_i8 v197, v55, v171, v197
	v_dot4_i32_i8 v198, v191, v170, v198
	v_dot4_i32_i8 v199, v59, v171, v199
	s_waitcnt vmcnt(24)
; __device__ __forceinline__ void u_compute(const u32x4 (&w)[16], const PeerVisit& v, int* pd, int lane) {
;     ...
;     for (int it = 0; it < 16; ++it) {
;         int tl = 0, th = 0;
;         tl = __builtin_amdgcn_sdot4((int)(w[it].x & 0x0F0F0F0Fu), (int)v.x.x, tl, false);  th = __builtin_amdgcn_sdot4((int)(w[it].x & 0xF0F0F0F0u), (int)v.x.y, th, false);
;         tl = __builtin_amdgcn_sdot4((int)(w[it].y & 0x0F0F0F0Fu), (int)v.x.z, tl, false);  th = __builtin_amdgcn_sdot4((int)(w[it].y & 0xF0F0F0F0u), (int)v.x.w, th, false);
;         tl = __builtin_amdgcn_sdot4((int)(w[it].z & 0x0F0F0F0Fu), (int)v.x2.x, tl, false); th = __builtin_amdgcn_sdot4((int)(w[it].z & 0xF0F0F0F0u), (int)v.x2.y, th, false);
;         tl = __builtin_amdgcn_sdot4((int)(w[it].w & 0x0F0F0F0Fu), (int)v.x2.z, tl, false); th = __builtin_amdgcn_sdot4((int)(w[it].w & 0xF0F0F0F0u), (int)v.x2.w, th, false);
;         const int t = tl * 16 + th;
;         d[it] = dpp_add8(t);
;     }
;     int v0 = d[0], v1 = d[8];
; #pragma unroll
;     for (int it = 1; it < 8; ++it) { v0 = (sub == it) ? d[it] : v0; v1 = (sub == it) ? d[8 + it] : v1; }
;     __builtin_nontemporal_store(v0, pd + pg * 16 + sub); __builtin_nontemporal_store(v1, pd + pg * 16 + 8 + sub);
; template <bool VPASS>
; __device__ __forceinline__ void peer_pass(Frame& F, int c, int rank, int nblk) {
;     ...
;     for (int v = 0; v < nvis; v += 2) {
;         const int tok = t0 + v * step;
;         asm volatile("" : "+v"(lane));
;         PeerVisit vn = va;
;         if (v + 1 < nvis) rows16_load(wb, T, vb, lane);
;         if (v + 2 < nvis) vn = visit_load<VPASS>(F.ws, FQc, tok + 2 * step, lane);
	v_and_b32_e32 v180, s61, v60
	v_and_b32_e32 v60, s62, v60
	v_and_b32_e32 v181, s61, v61
	v_and_b32_e32 v61, s62, v61
	v_and_b32_e32 v182, s61, v62
	v_and_b32_e32 v62, s62, v62
	v_and_b32_e32 v183, s61, v63
	v_and_b32_e32 v63, s62, v63
	v_lshl_add_u32 v160, v196, 4, v197
	v_lshl_add_u32 v161, v198, 4, v199
	v_and_b32_e32 v188, s61, v64
	v_and_b32_e32 v64, s62, v64
	v_and_b32_e32 v189, s61, v65
	v_and_b32_e32 v65, s62, v65
	v_and_b32_e32 v190, s61, v66
	v_and_b32_e32 v66, s62, v66
	v_and_b32_e32 v191, s61, v67
	v_and_b32_e32 v67, s62, v67
	v_dot4_i32_i8 v196, v180, v164, 0
	v_dot4_i32_i8 v197, v60, v165, 0
	v_dot4_i32_i8 v198, v188, v164, 0
	v_dot4_i32_i8 v199, v64, v165, 0
	v_dot4_i32_i8 v196, v181, v166, v196
	v_dot4_i32_i8 v197, v61, v167, v197
	v_dot4_i32_i8 v198, v189, v166, v198
	v_dot4_i32_i8 v199, v65, v167, v199
	v_dot4_i32_i8 v196, v182, v168, v196
	v_dot4_i32_i8 v197, v62, v169, v197
	v_dot4_i32_i8 v198, v190, v168, v198
	v_dot4_i32_i8 v199, v66, v169, v199
	v_dot4_i32_i8 v196, v183, v170, v196
	v_dot4_i32_i8 v197, v63, v171, v197
	v_dot4_i32_i8 v198, v191, v170, v198
	v_dot4_i32_i8 v199, v67, v171, v199
	s_add_i32 s93, s93, s39
	global_load_dwordx4 v[164:167], v2, s[44:45]
	global_load_dwordx4 v[168:171], v2, s[44:45] offset:16
	s_nop 1
	v_lshl_add_u32 v162, v196, 4, v197
	v_lshl_add_u32 v163, v198, 4, v199
	v_cndmask_b32_e64 v200, v148, v152, s[82:83]
	v_cndmask_b32_e64 v201, v152, v148, s[82:83]
	v_cndmask_b32_e64 v202, v149, v153, s[82:83]
	v_cndmask_b32_e64 v203, v153, v149, s[82:83]
	v_cndmask_b32_e64 v204, v150, v154, s[82:83]
	v_cndmask_b32_e64 v205, v154, v150, s[82:83]
	v_cndmask_b32_e64 v206, v151, v155, s[82:83]
	v_cndmask_b32_e64 v207, v155, v151, s[82:83]
	v_cndmask_b32_e64 v208, v156, v160, s[82:83]
	v_cndmask_b32_e64 v209, v160, v156, s[82:83]
	v_cndmask_b32_e64 v210, v157, v161, s[82:83]
	v_cndmask_b32_e64 v211, v161, v157, s[82:83]
	v_cndmask_b32_e64 v212, v158, v162, s[82:83]
	v_cndmask_b32_e64 v213, v162, v158, s[82:83]
	v_cndmask_b32_e64 v214, v159, v163, s[82:83]
	v_cndmask_b32_e64 v215, v163, v159, s[82:83]
	s_nop 1
	v_add_u32_dpp v200, v201, v200 row_half_mirror row_mask:0xf bank_mask:0xf bound_ctrl:1
	v_add_u32_dpp v202, v203, v202 row_half_mirror row_mask:0xf bank_mask:0xf bound_ctrl:1
	v_add_u32_dpp v204, v205, v204 row_half_mirror row_mask:0xf bank_mask:0xf bound_ctrl:1
	v_add_u32_dpp v206, v207, v206 row_half_mirror row_mask:0xf bank_mask:0xf bound_ctrl:1
	v_add_u32_dpp v208, v209, v208 row_half_mirror row_mask:0xf bank_mask:0xf bound_ctrl:1
	v_add_u32_dpp v210, v211, v210 row_half_mirror row_mask:0xf bank_mask:0xf bound_ctrl:1
	v_add_u32_dpp v212, v213, v212 row_half_mirror row_mask:0xf bank_mask:0xf bound_ctrl:1
	v_add_u32_dpp v214, v215, v214 row_half_mirror row_mask:0xf bank_mask:0xf bound_ctrl:1
	v_cndmask_b32_e64 v216, v200, v204, s[84:85]
	v_cndmask_b32_e64 v217, v204, v200, s[84:85]
	v_cndmask_b32_e64 v218, v202, v206, s[84:85]
	v_cndmask_b32_e64 v219, v206, v202, s[84:85]
	v_cndmask_b32_e64 v220, v208, v212, s[84:85]
	v_cndmask_b32_e64 v221, v212, v208, s[84:85]
	v_cndmask_b32_e64 v222, v210, v214, s[84:85]
	v_cndmask_b32_e64 v223, v214, v210, s[84:85]
	s_nop 1
	v_add_u32_dpp v216, v217, v216 quad_perm:[2,3,0,1] row_mask:0xf bank_mask:0xf bound_ctrl:1
	v_add_u32_dpp v218, v219, v218 quad_perm:[2,3,0,1] row_mask:0xf bank_mask:0xf bound_ctrl:1
	v_add_u32_dpp v220, v221, v220 quad_perm:[2,3,0,1] row_mask:0xf bank_mask:0xf bound_ctrl:1
	v_add_u32_dpp v222, v223, v222 quad_perm:[2,3,0,1] row_mask:0xf bank_mask:0xf bound_ctrl:1
	v_cndmask_b32_e64 v224, v216, v218, s[86:87]
	v_cndmask_b32_e64 v225, v218, v216, s[86:87]
	v_cndmask_b32_e64 v226, v220, v222, s[86:87]
	v_cndmask_b32_e64 v227, v222, v220, s[86:87]
	s_nop 1
	v_add_u32_dpp v224, v225, v224 quad_perm:[1,0,3,2] row_mask:0xf bank_mask:0xf bound_ctrl:1
	v_add_u32_dpp v226, v227, v226 quad_perm:[1,0,3,2] row_mask:0xf bank_mask:0xf bound_ctrl:1
	s_nop 1
	global_store_dword v3, v224, s[46:47] nt
	global_store_dword v3, v226, s[46:47] offset:32 nt
	s_add_u32 s46, s46, s48
	s_addc_u32 s47, s47, 0
	s_cmp_lt_i32 s93, 0x8000
	s_cbranch_scc0 .Lmy_u_done
	s_waitcnt vmcnt(20)
	v_lshl_add_u32 v180, v132, 7, v1
	v_lshl_add_u32 v181, v133, 7, v1
	v_lshl_add_u32 v182, v134, 7, v1
	v_lshl_add_u32 v183, v135, 7, v1
	v_lshl_add_u32 v184, v136, 7, v1
	v_lshl_add_u32 v185, v137, 7, v1
	v_lshl_add_u32 v186, v138, 7, v1
	v_lshl_add_u32 v187, v139, 7, v1
	v_lshl_add_u32 v188, v140, 7, v1
	v_lshl_add_u32 v189, v141, 7, v1
	v_lshl_add_u32 v190, v142, 7, v1
	v_lshl_add_u32 v191, v143, 7, v1
	v_lshl_add_u32 v192, v144, 7, v1
	v_lshl_add_u32 v193, v145, 7, v1
	v_lshl_add_u32 v194, v146, 7, v1
	v_lshl_add_u32 v195, v147, 7, v1
	s_add_i32 s38, s38, s39
	s_cmp_lt_i32 s38, 0x8000
	s_cselect_b32 s63, s48, 0
	s_cselect_b32 s71, s49, 0
	s_add_u32 s42, s42, s63
	s_addc_u32 s43, s43, 0
	s_add_u32 s44, s44, s71
	s_addc_u32 s45, s45, 0
	global_load_dwordx4 v[132:135], v0, s[42:43]
	global_load_dwordx4 v[136:139], v0, s[42:43] offset:16
	global_load_dwordx4 v[140:143], v0, s[42:43] offset:32
	global_load_dwordx4 v[144:147], v0, s[42:43] offset:48
	global_load_dwordx4 v[4:7], v180, s[40:41]
	global_load_dwordx4 v[8:11], v181, s[40:41]
	global_load_dwordx4 v[12:15], v182, s[40:41]
	global_load_dwordx4 v[16:19], v183, s[40:41]
	global_load_dwordx4 v[20:23], v184, s[40:41]
	global_load_dwordx4 v[24:27], v185, s[40:41]
	global_load_dwordx4 v[28:31], v186, s[40:41]
	global_load_dwordx4 v[32:35], v187, s[40:41]
	global_load_dwordx4 v[36:39], v188, s[40:41]
	global_load_dwordx4 v[40:43], v189, s[40:41]
	global_load_dwordx4 v[44:47], v190, s[40:41]
	global_load_dwordx4 v[48:51], v191, s[40:41]
	global_load_dwordx4 v[52:55], v192, s[40:41]
	global_load_dwordx4 v[56:59], v193, s[40:41]
	global_load_dwordx4 v[60:63], v194, s[40:41]
	global_load_dwordx4 v[64:67], v195, s[40:41]
	s_waitcnt vmcnt(38)
; __device__ __forceinline__ void u_compute(const u32x4 (&w)[16], const PeerVisit& v, int* pd, int lane) {
;     ...
;     for (int it = 0; it < 16; ++it) {
;         int tl = 0, th = 0;
;         tl = __builtin_amdgcn_sdot4((int)(w[it].x & 0x0F0F0F0Fu), (int)v.x.x, tl, false);  th = __builtin_amdgcn_sdot4((int)(w[it].x & 0xF0F0F0F0u), (int)v.x.y, th, false);
;         tl = __builtin_amdgcn_sdot4((int)(w[it].y & 0x0F0F0F0Fu), (int)v.x.z, tl, false);  th = __builtin_amdgcn_sdot4((int)(w[it].y & 0xF0F0F0F0u), (int)v.x.w, th, false);
;         tl = __builtin_amdgcn_sdot4((int)(w[it].z & 0x0F0F0F0Fu), (int)v.x2.x, tl, false); th = __builtin_amdgcn_sdot4((int)(w[it].z & 0xF0F0F0F0u), (int)v.x2.y, th, false);
;         tl = __builtin_amdgcn_sdot4((int)(w[it].w & 0x0F0F0F0Fu), (int)v.x2.z, tl, false); th = __builtin_amdgcn_sdot4((int)(w[it].w & 0xF0F0F0F0u), (int)v.x2.w, th, false);
;         const int t = tl * 16 + th;
;         d[it] = dpp_add8(t);
	v_and_b32_e32 v180, s61, v68
	v_and_b32_e32 v68, s62, v68
	v_and_b32_e32 v181, s61, v69
	v_and_b32_e32 v69, s62, v69
	v_and_b32_e32 v182, s61, v70
	v_and_b32_e32 v70, s62, v70
	v_and_b32_e32 v183, s61, v71
	v_and_b32_e32 v71, s62, v71
	v_and_b32_e32 v188, s61, v72
	v_and_b32_e32 v72, s62, v72
	v_and_b32_e32 v189, s61, v73
	v_and_b32_e32 v73, s62, v73
	v_and_b32_e32 v190, s61, v74
	v_and_b32_e32 v74, s62, v74
	v_and_b32_e32 v191, s61, v75
	v_and_b32_e32 v75, s62, v75
	v_dot4_i32_i8 v196, v180, v172, 0
	v_dot4_i32_i8 v197, v68, v173, 0
	v_dot4_i32_i8 v198, v188, v172, 0
	v_dot4_i32_i8 v199, v72, v173, 0
	v_dot4_i32_i8 v196, v181, v174, v196
	v_dot4_i32_i8 v197, v69, v175, v197
	v_dot4_i32_i8 v198, v189, v174, v198
	v_dot4_i32_i8 v199, v73, v175, v199
	v_dot4_i32_i8 v196, v182, v176, v196
	v_dot4_i32_i8 v197, v70, v177, v197
	v_dot4_i32_i8 v198, v190, v176, v198
	v_dot4_i32_i8 v199, v74, v177, v199
	v_dot4_i32_i8 v196, v183, v178, v196
	v_dot4_i32_i8 v197, v71, v179, v197
	v_dot4_i32_i8 v198, v191, v178, v198
	v_dot4_i32_i8 v199, v75, v179, v199
	s_waitcnt vmcnt(36)
	v_and_b32_e32 v180, s61, v76
	v_and_b32_e32 v76, s62, v76
	v_and_b32_e32 v181, s61, v77
	v_and_b32_e32 v77, s62, v77
	v_and_b32_e32 v182, s61, v78
	v_and_b32_e32 v78, s62, v78
	v_and_b32_e32 v183, s61, v79
	v_and_b32_e32 v79, s62, v79
	v_lshl_add_u32 v148, v196, 4, v197
	v_lshl_add_u32 v149, v198, 4, v199
	v_and_b32_e32 v188, s61, v80
	v_and_b32_e32 v80, s62, v80
	v_and_b32_e32 v189, s61, v81
	v_and_b32_e32 v81, s62, v81
	v_and_b32_e32 v190, s61, v82
	v_and_b32_e32 v82, s62, v82
	v_and_b32_e32 v191, s61, v83
	v_and_b32_e32 v83, s62, v83
	v_dot4_i32_i8 v196, v180, v172, 0
	v_dot4_i32_i8 v197, v76, v173, 0
	v_dot4_i32_i8 v198, v188, v172, 0
	v_dot4_i32_i8 v199, v80, v173, 0
	v_dot4_i32_i8 v196, v181, v174, v196
	v_dot4_i32_i8 v197, v77, v175, v197
	v_dot4_i32_i8 v198, v189, v174, v198
	v_dot4_i32_i8 v199, v81, v175, v199
	v_dot4_i32_i8 v196, v182, v176, v196
	v_dot4_i32_i8 v197, v78, v177, v197
	v_dot4_i32_i8 v198, v190, v176, v198
	v_dot4_i32_i8 v199, v82, v177, v199
	v_dot4_i32_i8 v196, v183, v178, v196
	v_dot4_i32_i8 v197, v79, v179, v197
	v_dot4_i32_i8 v198, v191, v178, v198
	v_dot4_i32_i8 v199, v83, v179, v199
	s_waitcnt vmcnt(34)
	v_and_b32_e32 v180, s61, v84
	v_and_b32_e32 v84, s62, v84
	v_and_b32_e32 v181, s61, v85
	v_and_b32_e32 v85, s62, v85
	v_and_b32_e32 v182, s61, v86
	v_and_b32_e32 v86, s62, v86
	v_and_b32_e32 v183, s61, v87
	v_and_b32_e32 v87, s62, v87
	v_lshl_add_u32 v150, v196, 4, v197
	v_lshl_add_u32 v151, v198, 4, v199
	v_and_b32_e32 v188, s61, v88
	v_and_b32_e32 v88, s62, v88
	v_and_b32_e32 v189, s61, v89
	v_and_b32_e32 v89, s62, v89
	v_and_b32_e32 v190, s61, v90
	v_and_b32_e32 v90, s62, v90
	v_and_b32_e32 v191, s61, v91
	v_and_b32_e32 v91, s62, v91
	v_dot4_i32_i8 v196, v180, v172, 0
	v_dot4_i32_i8 v197, v84, v173, 0
	v_dot4_i32_i8 v198, v188, v172, 0
	v_dot4_i32_i8 v199, v88, v173, 0
	v_dot4_i32_i8 v196, v181, v174, v196
	v_dot4_i32_i8 v197, v85, v175, v197
	v_dot4_i32_i8 v198, v189, v174, v198
	v_dot4_i32_i8 v199, v89, v175, v199
	v_dot4_i32_i8 v196, v182, v176, v196
	v_dot4_i32_i8 v197, v86, v177, v197
	v_dot4_i32_i8 v198, v190, v176, v198
	v_dot4_i32_i8 v199, v90, v177, v199
	v_dot4_i32_i8 v196, v183, v178, v196
	v_dot4_i32_i8 v197, v87, v179, v197
	v_dot4_i32_i8 v198, v191, v178, v198
	v_dot4_i32_i8 v199, v91, v179, v199
	s_waitcnt vmcnt(32)
	v_and_b32_e32 v180, s61, v92
	v_and_b32_e32 v92, s62, v92
	v_and_b32_e32 v181, s61, v93
	v_and_b32_e32 v93, s62, v93
	v_and_b32_e32 v182, s61, v94
	v_and_b32_e32 v94, s62, v94
	v_and_b32_e32 v183, s61, v95
	v_and_b32_e32 v95, s62, v95
	v_lshl_add_u32 v152, v196, 4, v197
	v_lshl_add_u32 v153, v198, 4, v199
	v_and_b32_e32 v188, s61, v96
	v_and_b32_e32 v96, s62, v96
	v_and_b32_e32 v189, s61, v97
	v_and_b32_e32 v97, s62, v97
	v_and_b32_e32 v190, s61, v98
	v_and_b32_e32 v98, s62, v98
	v_and_b32_e32 v191, s61, v99
	v_and_b32_e32 v99, s62, v99
	v_dot4_i32_i8 v196, v180, v172, 0
	v_dot4_i32_i8 v197, v92, v173, 0
	v_dot4_i32_i8 v198, v188, v172, 0
	v_dot4_i32_i8 v199, v96, v173, 0
	v_dot4_i32_i8 v196, v181, v174, v196
	v_dot4_i32_i8 v197, v93, v175, v197
	v_dot4_i32_i8 v198, v189, v174, v198
	v_dot4_i32_i8 v199, v97, v175, v199
	v_dot4_i32_i8 v196, v182, v176, v196
	v_dot4_i32_i8 v197, v94, v177, v197
	v_dot4_i32_i8 v198, v190, v176, v198
	v_dot4_i32_i8 v199, v98, v177, v199
	v_dot4_i32_i8 v196, v183, v178, v196
	v_dot4_i32_i8 v197, v95, v179, v197
	v_dot4_i32_i8 v198, v191, v178, v198
	v_dot4_i32_i8 v199, v99, v179, v199
	s_waitcnt vmcnt(30)
	v_and_b32_e32 v180, s61, v100
	v_and_b32_e32 v100, s62, v100
	v_and_b32_e32 v181, s61, v101
	v_and_b32_e32 v101, s62, v101
	v_and_b32_e32 v182, s61, v102
	v_and_b32_e32 v102, s62, v102
	v_and_b32_e32 v183, s61, v103
	v_and_b32_e32 v103, s62, v103
	v_lshl_add_u32 v154, v196, 4, v197
	v_lshl_add_u32 v155, v198, 4, v199
	v_and_b32_e32 v188, s61, v104
	v_and_b32_e32 v104, s62, v104
	v_and_b32_e32 v189, s61, v105
	v_and_b32_e32 v105, s62, v105
	v_and_b32_e32 v190, s61, v106
	v_and_b32_e32 v106, s62, v106
	v_and_b32_e32 v191, s61, v107
	v_and_b32_e32 v107, s62, v107
	v_dot4_i32_i8 v196, v180, v172, 0
	v_dot4_i32_i8 v197, v100, v173, 0
	v_dot4_i32_i8 v198, v188, v172, 0
	v_dot4_i32_i8 v199, v104, v173, 0
	v_dot4_i32_i8 v196, v181, v174, v196
	v_dot4_i32_i8 v197, v101, v175, v197
	v_dot4_i32_i8 v198, v189, v174, v198
	v_dot4_i32_i8 v199, v105, v175, v199
	v_dot4_i32_i8 v196, v182, v176, v196
	v_dot4_i32_i8 v197, v102, v177, v197
	v_dot4_i32_i8 v198, v190, v176, v198
	v_dot4_i32_i8 v199, v106, v177, v199
	v_dot4_i32_i8 v196, v183, v178, v196
	v_dot4_i32_i8 v197, v103, v179, v197
	v_dot4_i32_i8 v198, v191, v178, v198
	v_dot4_i32_i8 v199, v107, v179, v199
	s_waitcnt vmcnt(28)
; __device__ __forceinline__ void u_compute(const u32x4 (&w)[16], const PeerVisit& v, int* pd, int lane) {
;     ...
;     for (int it = 0; it < 16; ++it) {
;         int tl = 0, th = 0;
;         tl = __builtin_amdgcn_sdot4((int)(w[it].x & 0x0F0F0F0Fu), (int)v.x.x, tl, false);  th = __builtin_amdgcn_sdot4((int)(w[it].x & 0xF0F0F0F0u), (int)v.x.y, th, false);
;         tl = __builtin_amdgcn_sdot4((int)(w[it].y & 0x0F0F0F0Fu), (int)v.x.z, tl, false);  th = __builtin_amdgcn_sdot4((int)(w[it].y & 0xF0F0F0F0u), (int)v.x.w, th, false);
;         tl = __builtin_amdgcn_sdot4((int)(w[it].z & 0x0F0F0F0Fu), (int)v.x2.x, tl, false); th = __builtin_amdgcn_sdot4((int)(w[it].z & 0xF0F0F0F0u), (int)v.x2.y, th, false);
;         tl = __builtin_amdgcn_sdot4((int)(w[it].w & 0x0F0F0F0Fu), (int)v.x2.z, tl, false); th = __builtin_amdgcn_sdot4((int)(w[it].w & 0xF0F0F0F0u), (int)v.x2.w, th, false);
;         const int t = tl * 16 + th;
;         d[it] = dpp_add8(t);
;     }
;     int v0 = d[0], v1 = d[8];
; #pragma unroll
;     for (int it = 1; it < 8; ++it) { v0 = (sub == it) ? d[it] : v0; v1 = (sub == it) ? d[8 + it] : v1; }
;     __builtin_nontemporal_store(v0, pd + pg * 16 + sub); __builtin_nontemporal_store(v1, pd + pg * 16 + 8 + sub);
	v_and_b32_e32 v180, s61, v108
	v_and_b32_e32 v108, s62, v108
	v_and_b32_e32 v181, s61, v109
	v_and_b32_e32 v109, s62, v109
	v_and_b32_e32 v182, s61, v110
	v_and_b32_e32 v110, s62, v110
	v_and_b32_e32 v183, s61, v111
	v_and_b32_e32 v111, s62, v111
	v_lshl_add_u32 v156, v196, 4, v197
	v_lshl_add_u32 v157, v198, 4, v199
	v_and_b32_e32 v188, s61, v112
	v_and_b32_e32 v112, s62, v112
	v_and_b32_e32 v189, s61, v113
	v_and_b32_e32 v113, s62, v113
	v_and_b32_e32 v190, s61, v114
	v_and_b32_e32 v114, s62, v114
	v_and_b32_e32 v191, s61, v115
	v_and_b32_e32 v115, s62, v115
	v_dot4_i32_i8 v196, v180, v172, 0
	v_dot4_i32_i8 v197, v108, v173, 0
	v_dot4_i32_i8 v198, v188, v172, 0
	v_dot4_i32_i8 v199, v112, v173, 0
	v_dot4_i32_i8 v196, v181, v174, v196
	v_dot4_i32_i8 v197, v109, v175, v197
	v_dot4_i32_i8 v198, v189, v174, v198
	v_dot4_i32_i8 v199, v113, v175, v199
	v_dot4_i32_i8 v196, v182, v176, v196
	v_dot4_i32_i8 v197, v110, v177, v197
	v_dot4_i32_i8 v198, v190, v176, v198
	v_dot4_i32_i8 v199, v114, v177, v199
	v_dot4_i32_i8 v196, v183, v178, v196
	v_dot4_i32_i8 v197, v111, v179, v197
	v_dot4_i32_i8 v198, v191, v178, v198
	v_dot4_i32_i8 v199, v115, v179, v199
	s_waitcnt vmcnt(26)
	v_and_b32_e32 v180, s61, v116
	v_and_b32_e32 v116, s62, v116
	v_and_b32_e32 v181, s61, v117
	v_and_b32_e32 v117, s62, v117
	v_and_b32_e32 v182, s61, v118
	v_and_b32_e32 v118, s62, v118
	v_and_b32_e32 v183, s61, v119
	v_and_b32_e32 v119, s62, v119
	v_lshl_add_u32 v158, v196, 4, v197
	v_lshl_add_u32 v159, v198, 4, v199
	v_and_b32_e32 v188, s61, v120
	v_and_b32_e32 v120, s62, v120
	v_and_b32_e32 v189, s61, v121
	v_and_b32_e32 v121, s62, v121
	v_and_b32_e32 v190, s61, v122
	v_and_b32_e32 v122, s62, v122
	v_and_b32_e32 v191, s61, v123
	v_and_b32_e32 v123, s62, v123
	v_dot4_i32_i8 v196, v180, v172, 0
	v_dot4_i32_i8 v197, v116, v173, 0
	v_dot4_i32_i8 v198, v188, v172, 0
	v_dot4_i32_i8 v199, v120, v173, 0
	v_dot4_i32_i8 v196, v181, v174, v196
	v_dot4_i32_i8 v197, v117, v175, v197
	v_dot4_i32_i8 v198, v189, v174, v198
	v_dot4_i32_i8 v199, v121, v175, v199
	v_dot4_i32_i8 v196, v182, v176, v196
	v_dot4_i32_i8 v197, v118, v177, v197
	v_dot4_i32_i8 v198, v190, v176, v198
	v_dot4_i32_i8 v199, v122, v177, v199
	v_dot4_i32_i8 v196, v183, v178, v196
	v_dot4_i32_i8 v197, v119, v179, v197
	v_dot4_i32_i8 v198, v191, v178, v198
	v_dot4_i32_i8 v199, v123, v179, v199
	s_waitcnt vmcnt(24)
	v_and_b32_e32 v180, s61, v124
	v_and_b32_e32 v124, s62, v124
	v_and_b32_e32 v181, s61, v125
	v_and_b32_e32 v125, s62, v125
	v_and_b32_e32 v182, s61, v126
	v_and_b32_e32 v126, s62, v126
	v_and_b32_e32 v183, s61, v127
	v_and_b32_e32 v127, s62, v127
	v_lshl_add_u32 v160, v196, 4, v197
	v_lshl_add_u32 v161, v198, 4, v199
	v_and_b32_e32 v188, s61, v128
	v_and_b32_e32 v128, s62, v128
	v_and_b32_e32 v189, s61, v129
	v_and_b32_e32 v129, s62, v129
	v_and_b32_e32 v190, s61, v130
	v_and_b32_e32 v130, s62, v130
	v_and_b32_e32 v191, s61, v131
	v_and_b32_e32 v131, s62, v131
	v_dot4_i32_i8 v196, v180, v172, 0
	v_dot4_i32_i8 v197, v124, v173, 0
	v_dot4_i32_i8 v198, v188, v172, 0
	v_dot4_i32_i8 v199, v128, v173, 0
	v_dot4_i32_i8 v196, v181, v174, v196
	v_dot4_i32_i8 v197, v125, v175, v197
	v_dot4_i32_i8 v198, v189, v174, v198
	v_dot4_i32_i8 v199, v129, v175, v199
	v_dot4_i32_i8 v196, v182, v176, v196
	v_dot4_i32_i8 v197, v126, v177, v197
	v_dot4_i32_i8 v198, v190, v176, v198
	v_dot4_i32_i8 v199, v130, v177, v199
	v_dot4_i32_i8 v196, v183, v178, v196
	v_dot4_i32_i8 v197, v127, v179, v197
	v_dot4_i32_i8 v198, v191, v178, v198
	v_dot4_i32_i8 v199, v131, v179, v199
	s_add_i32 s93, s93, s39
	global_load_dwordx4 v[172:175], v2, s[44:45]
	global_load_dwordx4 v[176:179], v2, s[44:45] offset:16
	s_nop 1
	v_lshl_add_u32 v162, v196, 4, v197
	v_lshl_add_u32 v163, v198, 4, v199
	v_cndmask_b32_e64 v200, v148, v152, s[82:83]
	v_cndmask_b32_e64 v201, v152, v148, s[82:83]
	v_cndmask_b32_e64 v202, v149, v153, s[82:83]
	v_cndmask_b32_e64 v203, v153, v149, s[82:83]
	v_cndmask_b32_e64 v204, v150, v154, s[82:83]
	v_cndmask_b32_e64 v205, v154, v150, s[82:83]
	v_cndmask_b32_e64 v206, v151, v155, s[82:83]
	v_cndmask_b32_e64 v207, v155, v151, s[82:83]
	v_cndmask_b32_e64 v208, v156, v160, s[82:83]
	v_cndmask_b32_e64 v209, v160, v156, s[82:83]
	v_cndmask_b32_e64 v210, v157, v161, s[82:83]
	v_cndmask_b32_e64 v211, v161, v157, s[82:83]
	v_cndmask_b32_e64 v212, v158, v162, s[82:83]
	v_cndmask_b32_e64 v213, v162, v158, s[82:83]
	v_cndmask_b32_e64 v214, v159, v163, s[82:83]
	v_cndmask_b32_e64 v215, v163, v159, s[82:83]
	s_nop 1
	v_add_u32_dpp v200, v201, v200 row_half_mirror row_mask:0xf bank_mask:0xf bound_ctrl:1
	v_add_u32_dpp v202, v203, v202 row_half_mirror row_mask:0xf bank_mask:0xf bound_ctrl:1
	v_add_u32_dpp v204, v205, v204 row_half_mirror row_mask:0xf bank_mask:0xf bound_ctrl:1
	v_add_u32_dpp v206, v207, v206 row_half_mirror row_mask:0xf bank_mask:0xf bound_ctrl:1
	v_add_u32_dpp v208, v209, v208 row_half_mirror row_mask:0xf bank_mask:0xf bound_ctrl:1
	v_add_u32_dpp v210, v211, v210 row_half_mirror row_mask:0xf bank_mask:0xf bound_ctrl:1
	v_add_u32_dpp v212, v213, v212 row_half_mirror row_mask:0xf bank_mask:0xf bound_ctrl:1
	v_add_u32_dpp v214, v215, v214 row_half_mirror row_mask:0xf bank_mask:0xf bound_ctrl:1
	v_cndmask_b32_e64 v216, v200, v204, s[84:85]
	v_cndmask_b32_e64 v217, v204, v200, s[84:85]
	v_cndmask_b32_e64 v218, v202, v206, s[84:85]
	v_cndmask_b32_e64 v219, v206, v202, s[84:85]
	v_cndmask_b32_e64 v220, v208, v212, s[84:85]
	v_cndmask_b32_e64 v221, v212, v208, s[84:85]
	v_cndmask_b32_e64 v222, v210, v214, s[84:85]
	v_cndmask_b32_e64 v223, v214, v210, s[84:85]
	s_nop 1
	v_add_u32_dpp v216, v217, v216 quad_perm:[2,3,0,1] row_mask:0xf bank_mask:0xf bound_ctrl:1
	v_add_u32_dpp v218, v219, v218 quad_perm:[2,3,0,1] row_mask:0xf bank_mask:0xf bound_ctrl:1
	v_add_u32_dpp v220, v221, v220 quad_perm:[2,3,0,1] row_mask:0xf bank_mask:0xf bound_ctrl:1
	v_add_u32_dpp v222, v223, v222 quad_perm:[2,3,0,1] row_mask:0xf bank_mask:0xf bound_ctrl:1
	v_cndmask_b32_e64 v224, v216, v218, s[86:87]
	v_cndmask_b32_e64 v225, v218, v216, s[86:87]
	v_cndmask_b32_e64 v226, v220, v222, s[86:87]
	v_cndmask_b32_e64 v227, v222, v220, s[86:87]
	s_nop 1
	v_add_u32_dpp v224, v225, v224 quad_perm:[1,0,3,2] row_mask:0xf bank_mask:0xf bound_ctrl:1
	v_add_u32_dpp v226, v227, v226 quad_perm:[1,0,3,2] row_mask:0xf bank_mask:0xf bound_ctrl:1
	s_nop 1
	global_store_dword v3, v224, s[46:47] nt
	global_store_dword v3, v226, s[46:47] offset:32 nt
	s_add_u32 s46, s46, s48
	s_addc_u32 s47, s47, 0
	s_cmp_lt_i32 s93, 0x8000
	s_cbranch_scc0 .Lmy_u_done
	s_waitcnt vmcnt(20)
	s_branch .Lmy_u_loop
